# S5: direction-0 E-operand loads issued in the unit prologue behind the U-tile loads
# baseline (speedup 1.0000x reference)
.LBB0_718:
	s_and_b32 s7, s17, 31
	s_add_i32 s88, s16, s7
	s_and_b32 s23, s6, 31
	s_lshl_b64 s[8:9], s[88:89], 18
	s_or_b32 s88, s23, s16
	s_ashr_i32 s7, s6, 31
	s_lshl_b64 s[10:11], s[88:89], 18
	s_lshl_b64 s[24:25], s[6:7], 16
	s_add_u32 s24, s12, s24
	s_addc_u32 s25, s13, s25
	v_lshl_add_u64 v[0:1], s[24:25], 0, v[120:121]
	s_barrier
	global_load_dwordx4 v[0:3], v[0:1], off
	v_lshl_add_u64 v[4:5], s[24:25], 0, v[122:123]
	global_load_dwordx4 v[4:7], v[4:5], off
	v_lshl_add_u64 v[8:9], s[24:25], 0, v[124:125]
	global_load_dwordx4 v[8:11], v[8:9], off
	v_lshl_add_u64 v[12:13], s[24:25], 0, v[126:127]
	global_load_dwordx4 v[12:15], v[12:13], off
	v_lshl_add_u64 v[16:17], s[24:25], 0, v[128:129]
	global_load_dwordx4 v[16:19], v[16:17], off
	v_lshl_add_u64 v[20:21], s[24:25], 0, v[130:131]
	global_load_dwordx4 v[20:23], v[20:21], off
	v_lshl_add_u64 v[24:25], s[24:25], 0, v[132:133]
	global_load_dwordx4 v[24:27], v[24:25], off
	v_lshl_add_u64 v[28:29], s[24:25], 0, v[134:135]
	global_load_dwordx4 v[28:31], v[28:29], off
	v_mov_b32_e32 v32, v33
	v_mov_b32_e32 v46, v33
	v_mov_b32_e32 v47, v33
	s_lshl_b64 s[24:25], s[88:89], 17
	s_waitcnt vmcnt(17)
	v_mov_b32_e32 v34, v33
	v_mov_b32_e32 v35, v33
	v_mov_b32_e32 v36, v33
	v_mov_b32_e32 v37, v33
	s_waitcnt vmcnt(16)
	v_mov_b32_e32 v38, v33
	v_mov_b32_e32 v39, v33
	v_mov_b32_e32 v40, v33
	v_mov_b32_e32 v41, v33
	v_mov_b32_e32 v42, v33
	v_mov_b32_e32 v43, v33
	v_mov_b32_e32 v44, v33
	v_mov_b32_e32 v45, v33
	s_waitcnt vmcnt(12)
	v_mov_b64_e32 v[78:79], v[46:47]
	v_mov_b64_e32 v[62:63], v[46:47]
	v_lshl_add_u64 v[148:149], v[112:113], 0, s[10:11]
	v_lshl_add_u64 v[150:151], v[116:117], 0, s[24:25]
	v_lshl_add_u32 v147, s88, 8, v143
	v_lshl_add_u64 v[152:153], v[144:145], 0, s[8:9]
	s_mov_b32 s88, 0
	v_lshlrev_b32_e32 v246, 8, v119
	v_ashrrev_i32_e32 v247, 31, v246
	v_lshl_add_u64 v[246:247], v[246:247], 1, v[150:151]
	global_load_dwordx4 v[166:169], v[246:247], off
	global_load_dwordx4 v[170:173], v[246:247], off offset:32
	global_load_dwordx4 v[174:177], v[246:247], off offset:64
	global_load_dwordx4 v[190:193], v[246:247], off offset:96
	global_load_dwordx4 v[194:197], v[246:247], off offset:128
	global_load_dwordx4 v[198:201], v[246:247], off offset:160
	global_load_dwordx4 v[202:205], v[246:247], off offset:192
	global_load_dwordx4 v[206:209], v[246:247], off offset:224
	global_load_dwordx4 v[234:237], v[246:247], off offset:256
	global_load_dwordx4 v[238:241], v[246:247], off offset:288
	global_load_dwordx4 v[242:245], v[246:247], off offset:320
	s_mov_b64 s[10:11], -1
	v_mov_b64_e32 v[76:77], v[44:45]
	v_mov_b64_e32 v[74:75], v[42:43]
	v_mov_b64_e32 v[72:73], v[40:41]
	v_mov_b64_e32 v[70:71], v[38:39]
	v_mov_b64_e32 v[68:69], v[36:37]
	v_mov_b64_e32 v[66:67], v[34:35]
	v_mov_b64_e32 v[64:65], v[32:33]
	v_mov_b64_e32 v[60:61], v[44:45]
	v_mov_b64_e32 v[58:59], v[42:43]
	v_mov_b64_e32 v[56:57], v[40:41]
	v_mov_b64_e32 v[54:55], v[38:39]
	v_mov_b64_e32 v[52:53], v[36:37]
	v_mov_b64_e32 v[50:51], v[34:35]
	v_mov_b64_e32 v[48:49], v[32:33]
	s_waitcnt vmcnt(18)
	ds_write_b128 v157, v[0:3]
	s_waitcnt vmcnt(17)
	ds_write_b128 v158, v[4:7]
	s_waitcnt vmcnt(16)
	ds_write_b128 v159, v[8:11]
	s_waitcnt vmcnt(15)
	ds_write_b128 v160, v[12:15]
	s_waitcnt vmcnt(14)
	ds_write_b128 v161, v[16:19]
	s_waitcnt vmcnt(13)
	ds_write_b128 v162, v[20:23]
	s_waitcnt vmcnt(12)
	ds_write_b128 v163, v[24:27]
	s_waitcnt vmcnt(11)
	ds_write_b128 v164, v[28:31]
	v_mov_b64_e32 v[16:17], v[32:33]
	v_mov_b64_e32 v[0:1], v[32:33]
	v_mov_b64_e32 v[18:19], v[34:35]
	v_mov_b64_e32 v[20:21], v[36:37]
	v_mov_b64_e32 v[22:23], v[38:39]
	v_mov_b64_e32 v[24:25], v[40:41]
	v_mov_b64_e32 v[26:27], v[42:43]
	v_mov_b64_e32 v[28:29], v[44:45]
	v_mov_b64_e32 v[30:31], v[46:47]
	v_mov_b64_e32 v[2:3], v[34:35]
	v_mov_b64_e32 v[4:5], v[36:37]
	v_mov_b64_e32 v[6:7], v[38:39]
	v_mov_b64_e32 v[8:9], v[40:41]
	v_mov_b64_e32 v[10:11], v[42:43]
	v_mov_b64_e32 v[12:13], v[44:45]
	v_mov_b64_e32 v[14:15], v[46:47]
	s_waitcnt lgkmcnt(0)
	s_barrier
.LBB0_719:
	v_add_lshl_u32 v34, v119, s88, 8
	v_ashrrev_i32_e32 v35, 31, v34
	v_lshl_add_u64 v[34:35], v[34:35], 1, v[150:151]
	s_and_b64 s[30:31], s[10:11], exec
	s_cbranch_scc1 .Ls5_eu_early
	global_load_dwordx4 v[166:169], v[34:35], off
	global_load_dwordx4 v[170:173], v[34:35], off offset:32
	global_load_dwordx4 v[174:177], v[34:35], off offset:64
	global_load_dwordx4 v[190:193], v[34:35], off offset:96
	global_load_dwordx4 v[194:197], v[34:35], off offset:128
	global_load_dwordx4 v[198:201], v[34:35], off offset:160
	global_load_dwordx4 v[202:205], v[34:35], off offset:192
	global_load_dwordx4 v[206:209], v[34:35], off offset:224
	global_load_dwordx4 v[234:237], v[34:35], off offset:256
	global_load_dwordx4 v[238:241], v[34:35], off offset:288
	global_load_dwordx4 v[242:245], v[34:35], off offset:320
.Ls5_eu_early:
	global_load_dwordx4 v[44:47], v[34:35], off offset:352
	v_add_u32_e32 v32, v139, v141
	ds_read_b128 v[36:39], v32
	ds_read_b128 v[40:43], v32 offset:16896
	ds_read_b128 v[246:249], v32 offset:32
	ds_read_b128 v[250:253], v32 offset:16928
	s_waitcnt vmcnt(11) lgkmcnt(3)
	v_mfma_f32_32x32x16_bf16 v[96:111], v[166:169], v[36:39], 0
	ds_read_b128 v[36:39], v32 offset:64
	s_waitcnt lgkmcnt(3)
	v_mfma_f32_32x32x16_bf16 v[80:95], v[166:169], v[40:43], 0
	ds_read_b128 v[40:43], v32 offset:16960
	s_waitcnt vmcnt(10) lgkmcnt(3)
	v_mfma_f32_32x32x16_bf16 v[96:111], v[170:173], v[246:249], v[96:111]
	ds_read_b128 v[246:249], v32 offset:96
	s_waitcnt lgkmcnt(3)
	v_mfma_f32_32x32x16_bf16 v[80:95], v[170:173], v[250:253], v[80:95]
	ds_read_b128 v[250:253], v32 offset:16992
	global_load_dwordx4 v[166:169], v[34:35], off offset:384
	s_waitcnt vmcnt(10) lgkmcnt(3)
	v_mfma_f32_32x32x16_bf16 v[96:111], v[174:177], v[36:39], v[96:111]
	ds_read_b128 v[36:39], v32 offset:128
	s_waitcnt lgkmcnt(3)
	v_mfma_f32_32x32x16_bf16 v[80:95], v[174:177], v[40:43], v[80:95]
	ds_read_b128 v[40:43], v32 offset:17024
	global_load_dwordx4 v[170:173], v[34:35], off offset:416
	s_waitcnt vmcnt(10) lgkmcnt(3)
	v_mfma_f32_32x32x16_bf16 v[96:111], v[190:193], v[246:249], v[96:111]
	ds_read_b128 v[246:249], v32 offset:160
	s_waitcnt lgkmcnt(3)
	v_mfma_f32_32x32x16_bf16 v[80:95], v[190:193], v[250:253], v[80:95]
	ds_read_b128 v[250:253], v32 offset:17056
	global_load_dwordx4 v[174:177], v[34:35], off offset:448
	s_waitcnt vmcnt(10) lgkmcnt(3)
	v_mfma_f32_32x32x16_bf16 v[96:111], v[194:197], v[36:39], v[96:111]
	ds_read_b128 v[36:39], v32 offset:192
	s_waitcnt lgkmcnt(3)
	v_mfma_f32_32x32x16_bf16 v[80:95], v[194:197], v[40:43], v[80:95]
	ds_read_b128 v[40:43], v32 offset:17088
	global_load_dwordx4 v[190:193], v[34:35], off offset:480
	s_waitcnt vmcnt(10) lgkmcnt(3)
	v_mfma_f32_32x32x16_bf16 v[96:111], v[198:201], v[246:249], v[96:111]
	ds_read_b128 v[246:249], v32 offset:224
	s_waitcnt lgkmcnt(3)
	v_mfma_f32_32x32x16_bf16 v[80:95], v[198:201], v[250:253], v[80:95]
	ds_read_b128 v[250:253], v32 offset:17120
	s_waitcnt vmcnt(9) lgkmcnt(3)
	v_mfma_f32_32x32x16_bf16 v[96:111], v[202:205], v[36:39], v[96:111]
	ds_read_b128 v[36:39], v32 offset:256
	s_waitcnt lgkmcnt(3)
	v_mfma_f32_32x32x16_bf16 v[80:95], v[202:205], v[40:43], v[80:95]
	ds_read_b128 v[40:43], v32 offset:17152
	s_waitcnt vmcnt(8) lgkmcnt(3)
	v_mfma_f32_32x32x16_bf16 v[96:111], v[206:209], v[246:249], v[96:111]
	ds_read_b128 v[246:249], v32 offset:288
	s_waitcnt lgkmcnt(3)
	v_mfma_f32_32x32x16_bf16 v[80:95], v[206:209], v[250:253], v[80:95]
	ds_read_b128 v[250:253], v32 offset:17184
	s_waitcnt vmcnt(7) lgkmcnt(3)
	v_mfma_f32_32x32x16_bf16 v[96:111], v[234:237], v[36:39], v[96:111]
	ds_read_b128 v[36:39], v32 offset:320
	s_waitcnt lgkmcnt(3)
	v_mfma_f32_32x32x16_bf16 v[80:95], v[234:237], v[40:43], v[80:95]
	ds_read_b128 v[40:43], v32 offset:17216
	s_waitcnt vmcnt(6) lgkmcnt(3)
	v_mfma_f32_32x32x16_bf16 v[96:111], v[238:241], v[246:249], v[96:111]
	ds_read_b128 v[246:249], v32 offset:352
	s_waitcnt lgkmcnt(3)
	v_mfma_f32_32x32x16_bf16 v[80:95], v[238:241], v[250:253], v[80:95]
	ds_read_b128 v[250:253], v32 offset:17248
	s_waitcnt vmcnt(5) lgkmcnt(3)
	v_mfma_f32_32x32x16_bf16 v[96:111], v[242:245], v[36:39], v[96:111]
	ds_read_b128 v[36:39], v32 offset:384
	s_waitcnt lgkmcnt(3)
	v_mfma_f32_32x32x16_bf16 v[80:95], v[242:245], v[40:43], v[80:95]
	ds_read_b128 v[40:43], v32 offset:17280
	s_waitcnt vmcnt(4) lgkmcnt(3)
	v_mfma_f32_32x32x16_bf16 v[96:111], v[44:47], v[246:249], v[96:111]
	ds_read_b128 v[246:249], v32 offset:416
	s_waitcnt lgkmcnt(3)
	v_mfma_f32_32x32x16_bf16 v[80:95], v[44:47], v[250:253], v[80:95]
	ds_read_b128 v[250:253], v32 offset:17312
	s_waitcnt vmcnt(3) lgkmcnt(3)
	v_mfma_f32_32x32x16_bf16 v[96:111], v[166:169], v[36:39], v[96:111]
	ds_read_b128 v[36:39], v32 offset:448
	s_waitcnt lgkmcnt(3)
	v_mfma_f32_32x32x16_bf16 v[80:95], v[166:169], v[40:43], v[80:95]
	ds_read_b128 v[40:43], v32 offset:17344
	s_waitcnt vmcnt(2) lgkmcnt(3)
	v_mfma_f32_32x32x16_bf16 v[96:111], v[170:173], v[246:249], v[96:111]
	ds_read_b128 v[246:249], v32 offset:480
	s_waitcnt lgkmcnt(3)
	v_mfma_f32_32x32x16_bf16 v[80:95], v[170:173], v[250:253], v[80:95]
	ds_read_b128 v[250:253], v32 offset:17376
	s_waitcnt vmcnt(1) lgkmcnt(3)
	v_mfma_f32_32x32x16_bf16 v[96:111], v[174:177], v[36:39], v[96:111]
	s_waitcnt lgkmcnt(2)
	v_mfma_f32_32x32x16_bf16 v[80:95], v[174:177], v[40:43], v[80:95]
	s_waitcnt vmcnt(0) lgkmcnt(1)
	v_mfma_f32_32x32x16_bf16 v[96:111], v[190:193], v[246:249], v[96:111]
	s_waitcnt lgkmcnt(0)
	v_mfma_f32_32x32x16_bf16 v[80:95], v[190:193], v[250:253], v[80:95]
	s_nop 11
	ds_write_b128 v165, v[96:99]
	ds_write_b128 v165, v[100:103] offset:32
	ds_write_b128 v165, v[104:107] offset:64
	ds_write_b128 v165, v[108:111] offset:96
	ds_write_b128 v165, v[80:83] offset:16896
	ds_write_b128 v165, v[84:87] offset:16928
	ds_write_b128 v165, v[88:91] offset:16960
	ds_write_b128 v165, v[92:95] offset:16992
	s_waitcnt lgkmcnt(0)
	s_barrier
	s_and_b64 s[30:31], s[10:11], exec
	s_cbranch_scc0 .Ls5_nopf
	global_load_dwordx4 v[100:103], v[148:149], off
	global_load_dwordx4 v[104:107], v[148:149], off offset:32
	global_load_dwordx4 v[108:111], v[148:149], off offset:64
	global_load_dwordx4 v[166:169], v[148:149], off offset:96
	global_load_dwordx4 v[170:173], v[148:149], off offset:128
	global_load_dwordx4 v[174:177], v[148:149], off offset:160
	global_load_dwordx4 v[190:193], v[148:149], off offset:192
	global_load_dwordx4 v[194:197], v[148:149], off offset:224
	global_load_dwordx4 v[198:201], v[148:149], off offset:256
	global_load_dwordx4 v[202:205], v[148:149], off offset:288
	global_load_dwordx4 v[206:209], v[148:149], off offset:320
	global_load_dwordx4 v[234:237], v[148:149], off offset:352
	global_load_dwordx4 v[238:241], v[148:149], off offset:384
	global_load_dwordx4 v[242:245], v[148:149], off offset:416
	global_load_dwordx4 v[246:249], v[148:149], off offset:448
	global_load_dwordx4 v[250:253], v[148:149], off offset:480
